# v67 = v66 + select: q rows loaded coalesced (8KB contiguous per wave step) and redistributed lane=row through wave-private LDS staging
# baseline (speedup 1.0000x reference)
.LBB0_161:
	s_or_b64 exec, exec, s[0:1]
	s_cmpk_lt_i32 s2, 0x100
	s_cselect_b64 s[40:41], -1, 0
	s_cmpk_gt_i32 s2, 0xff
	s_barrier
	s_cbranch_scc1 .LBB0_187
	v_lshlrev_b64 v[0:1], v189, -1
	v_readlane_b32 s8, v254, 57
	v_not_b32_e32 v64, v0
	v_mov_b32_e32 v131, 0
	v_readlane_b32 s12, v254, 61
	v_readlane_b32 s13, v254, 62
	v_mbcnt_lo_u32_b32 v0, -1, 0
	v_xor_b32_e32 v68, 15, v196
	v_cmp_gt_u32_e64 s[4:5], 64, v189
	v_lshlrev_b32_e32 v200, 4, v189
	v_or_b32_e32 v200, 0x1000, v200
	v_mul_u32_u24_e32 v202, 0x90, v189
	v_mul_u32_u24_e32 v201, 0x2400, v196
	v_add_u32_e32 v201, 0x1000, v201
	v_add_u32_e32 v202, v202, v201
	v_lshrrev_b32_e32 v203, 3, v189
	v_mul_u32_u24_e32 v203, 0x90, v203
	v_add_u32_e32 v201, v201, v203
	v_and_b32_e32 v203, 7, v189
	v_lshl_add_u32 v201, v203, 4, v201
	v_not_b32_e32 v65, v1
	v_lshl_or_b32 v69, v196, 8, v189
	v_add_u32_e32 v70, 0xfffffe00, v188
	v_add_u32_e32 v71, 0, v130
	v_lshl_add_u64 v[66:67], s[12:13], 0, v[130:131]
	v_mbcnt_hi_u32_b32 v72, -1, v0
	v_mov_b32_e32 v73, 0x2000
	v_mov_b32_e32 v74, 0x1000
	s_mov_b32 s33, s2
	v_readlane_b32 s9, v254, 58
	v_readlane_b32 s10, v254, 59
	v_readlane_b32 s11, v254, 60
	v_readlane_b32 s14, v254, 63
	v_readlane_b32 s15, v255, 0
	v_readlane_b32 s16, v255, 1
	v_readlane_b32 s17, v255, 2
	v_readlane_b32 s18, v255, 3
	v_readlane_b32 s19, v255, 4
	v_readlane_b32 s20, v255, 5
	v_readlane_b32 s21, v255, 6
	v_readlane_b32 s22, v255, 7
	v_readlane_b32 s23, v255, 8
	s_branch .LBB0_164

.LBB0_165:
	global_load_dword v4, v[0:1], off
	v_add_co_u32_e32 v3, vcc, 0x200, v3
	s_mov_b64 s[8:9], 0x800
	v_lshl_add_u64 v[0:1], v[0:1], 0, s[8:9]
	s_xor_b64 s[8:9], vcc, -1
	s_and_b64 s[8:9], exec, s[8:9]
	s_or_b64 s[6:7], s[8:9], s[6:7]
	s_waitcnt vmcnt(0)
	ds_write_b32 v2, v4
	v_add_u32_e32 v2, 0x800, v2
	s_andn2_b64 exec, exec, s[6:7]
	s_cbranch_execnz .LBB0_165
	s_or_b64 exec, exec, s[6:7]
	s_and_b32 s1, s33, 1
	v_lshl_or_b32 v0, s1, 7, v69
	v_or_b32_e32 v0, s10, v0
	v_and_b32_e32 v0, -64, v0
	v_mov_b32_e32 v1, s11
	v_lshlrev_b64 v[0:1], 7, v[0:1]
	v_or_b32_e32 v0, v0, v200
	v_lshl_add_u64 v[0:1], s[64:65], 0, v[0:1]
	s_waitcnt lgkmcnt(0)
	s_barrier
	global_load_dwordx4 v[60:63], v[0:1], off offset:-4096
	global_load_dwordx4 v[56:59], v[0:1], off offset:-3072
	global_load_dwordx4 v[52:55], v[0:1], off offset:-2048
	global_load_dwordx4 v[48:51], v[0:1], off offset:-1024
	global_load_dwordx4 v[44:47], v[0:1], off
	global_load_dwordx4 v[40:43], v[0:1], off offset:1024
	global_load_dwordx4 v[36:39], v[0:1], off offset:2048
	global_load_dwordx4 v[32:35], v[0:1], off offset:3072
	s_waitcnt vmcnt(0)
	ds_write_b128 v201, v[60:63]
	ds_write_b128 v201, v[56:59] offset:1152
	ds_write_b128 v201, v[52:55] offset:2304
	ds_write_b128 v201, v[48:51] offset:3456
	ds_write_b128 v201, v[44:47] offset:4608
	ds_write_b128 v201, v[40:43] offset:5760
	ds_write_b128 v201, v[36:39] offset:6912
	ds_write_b128 v201, v[32:35] offset:8064
	s_waitcnt lgkmcnt(0)
	ds_read_b128 v[60:63], v202
	ds_read_b128 v[56:59], v202 offset:16
	ds_read_b128 v[52:55], v202 offset:32
	ds_read_b128 v[48:51], v202 offset:48
	ds_read_b128 v[44:47], v202 offset:64
	ds_read_b128 v[40:43], v202 offset:80
	ds_read_b128 v[36:39], v202 offset:96
	ds_read_b128 v[32:35], v202 offset:112
	s_waitcnt lgkmcnt(0)
	s_lshl_b32 s0, s0, 4
	s_lshl_b32 s34, s1, 1
	s_ashr_i32 s1, s0, 31
	v_readlane_b32 s12, v254, 57
	s_lshl_b64 s[6:7], s[0:1], 2
	v_readlane_b32 s22, v255, 3
	v_readlane_b32 s13, v254, 58
	v_readlane_b32 s23, v255, 4
	s_add_u32 s12, s22, s6
	v_readlane_b32 s14, v254, 59
	v_readlane_b32 s24, v255, 5
	s_addc_u32 s13, s23, s7
	s_lshl_b64 s[0:1], s[0:1], 13
	v_readlane_b32 s15, v254, 60
	v_readlane_b32 s20, v255, 1
	v_readlane_b32 s25, v255, 6
	s_add_u32 s14, s24, s0
	s_addc_u32 s15, s25, s1
	s_mov_b32 s20, 0
	v_readlane_b32 s16, v254, 61
	v_readlane_b32 s17, v254, 62
	v_readlane_b32 s18, v254, 63
	v_readlane_b32 s19, v255, 0
	v_readlane_b32 s21, v255, 2
	v_readlane_b32 s26, v255, 7
	v_readlane_b32 s27, v255, 8
	s_branch .LBB0_168
.LBB0_167:
	s_or_b64 exec, exec, s[16:17]
	s_cmp_eq_u32 s35, 4
	s_mov_b32 s20, s35
	s_waitcnt vmcnt(0)
	ds_write_b128 v201, v[28:31]
	ds_write_b128 v201, v[24:27] offset:1152
	ds_write_b128 v201, v[20:23] offset:2304
	ds_write_b128 v201, v[16:19] offset:3456
	ds_write_b128 v201, v[12:15] offset:4608
	ds_write_b128 v201, v[8:11] offset:5760
	ds_write_b128 v201, v[4:7] offset:6912
	ds_write_b128 v201, v[0:3] offset:8064
	s_waitcnt lgkmcnt(0)
	ds_read_b128 v[60:63], v202
	ds_read_b128 v[56:59], v202 offset:16
	ds_read_b128 v[52:55], v202 offset:32
	ds_read_b128 v[48:51], v202 offset:48
	ds_read_b128 v[44:47], v202 offset:64
	ds_read_b128 v[40:43], v202 offset:80
	ds_read_b128 v[36:39], v202 offset:96
	ds_read_b128 v[32:35], v202 offset:112
	s_waitcnt lgkmcnt(0)
	s_cbranch_scc1 .LBB0_163
.LBB0_168:
	s_cmp_lt_u32 s20, 2
	s_cselect_b64 vcc, -1, 0
	s_add_i32 s35, s20, 1
	s_cmp_lg_u32 s20, 3
	s_cselect_b32 s6, s35, 3
	s_cmp_lt_u32 s6, 2
	s_cselect_b64 s[0:1], -1, 0
	v_cndmask_b32_e64 v0, v68, v196, s[0:1]
	s_and_b32 s0, s6, 1
	s_or_b32 s0, s0, s34
	s_lshl_b32 s0, s0, 6
	v_lshl_or_b32 v0, v0, 8, s0
	v_or_b32_e32 v0, s10, v0
	v_mov_b32_e32 v1, s11
	v_lshlrev_b64 v[0:1], 7, v[0:1]
	v_or_b32_e32 v0, v0, v200
	v_lshl_add_u64 v[0:1], s[64:65], 0, v[0:1]
	global_load_dwordx4 v[28:31], v[0:1], off offset:-4096
	global_load_dwordx4 v[24:27], v[0:1], off offset:-3072
	global_load_dwordx4 v[20:23], v[0:1], off offset:-2048
	global_load_dwordx4 v[16:19], v[0:1], off offset:-1024
	global_load_dwordx4 v[12:15], v[0:1], off
	global_load_dwordx4 v[8:11], v[0:1], off offset:1024
	global_load_dwordx4 v[4:7], v[0:1], off offset:2048
	s_nop 0
	global_load_dwordx4 v[0:3], v[0:1], off offset:3072
	v_cndmask_b32_e32 v75, v68, v196, vcc
	v_cmp_ne_u32_e32 vcc, 0, v75
	s_and_saveexec_b64 s[16:17], vcc
	s_cbranch_execz .LBB0_167
	s_waitcnt vmcnt(15)
	v_lshlrev_b32_e32 v76, 16, v60
	v_and_b32_e32 v60, 0xffff0000, v60
	v_lshlrev_b32_e32 v77, 16, v61
	v_and_b32_e32 v61, 0xffff0000, v61
	v_lshlrev_b32_e32 v78, 16, v62
	v_and_b32_e32 v62, 0xffff0000, v62
	v_lshlrev_b32_e32 v79, 16, v63
	v_and_b32_e32 v63, 0xffff0000, v63
	s_waitcnt vmcnt(14)
	v_lshlrev_b32_e32 v80, 16, v56
	v_and_b32_e32 v56, 0xffff0000, v56
	v_lshlrev_b32_e32 v81, 16, v57
	v_and_b32_e32 v57, 0xffff0000, v57
	v_lshlrev_b32_e32 v82, 16, v58
	v_and_b32_e32 v58, 0xffff0000, v58
	v_lshlrev_b32_e32 v83, 16, v59
	v_and_b32_e32 v59, 0xffff0000, v59
	s_waitcnt vmcnt(13)
	v_lshlrev_b32_e32 v84, 16, v52
	v_and_b32_e32 v52, 0xffff0000, v52
	v_lshlrev_b32_e32 v85, 16, v53
	v_and_b32_e32 v53, 0xffff0000, v53
	v_lshlrev_b32_e32 v86, 16, v54
	v_and_b32_e32 v54, 0xffff0000, v54
	v_lshlrev_b32_e32 v87, 16, v55
	v_and_b32_e32 v55, 0xffff0000, v55
	s_waitcnt vmcnt(12)
	v_lshlrev_b32_e32 v88, 16, v48
	v_and_b32_e32 v48, 0xffff0000, v48
	v_lshlrev_b32_e32 v89, 16, v49
	v_and_b32_e32 v49, 0xffff0000, v49
	v_lshlrev_b32_e32 v90, 16, v50
	v_and_b32_e32 v50, 0xffff0000, v50
	v_lshlrev_b32_e32 v91, 16, v51
	v_and_b32_e32 v51, 0xffff0000, v51
	s_waitcnt vmcnt(11)
	v_lshlrev_b32_e32 v92, 16, v44
	v_and_b32_e32 v93, 0xffff0000, v44
	v_lshlrev_b32_e32 v94, 16, v45
	v_and_b32_e32 v95, 0xffff0000, v45
	v_lshlrev_b32_e32 v96, 16, v46
	v_and_b32_e32 v46, 0xffff0000, v46
	v_lshlrev_b32_e32 v97, 16, v47
	v_and_b32_e32 v47, 0xffff0000, v47
	s_waitcnt vmcnt(10)
	v_lshlrev_b32_e32 v98, 16, v40
	v_and_b32_e32 v99, 0xffff0000, v40
	v_lshlrev_b32_e32 v100, 16, v41
	v_and_b32_e32 v101, 0xffff0000, v41
	v_lshlrev_b32_e32 v102, 16, v42
	v_and_b32_e32 v103, 0xffff0000, v42
	v_lshlrev_b32_e32 v104, 16, v43
	v_and_b32_e32 v105, 0xffff0000, v43
	s_waitcnt vmcnt(9)
	v_lshlrev_b32_e32 v106, 16, v36
	v_and_b32_e32 v107, 0xffff0000, v36
	v_lshlrev_b32_e32 v108, 16, v37
	v_and_b32_e32 v109, 0xffff0000, v37
	v_and_b32_e32 v37, 0xffff0000, v38
	v_lshlrev_b32_e32 v36, 16, v38
	v_and_b32_e32 v41, 0xffff0000, v39
	v_lshlrev_b32_e32 v40, 16, v39
	s_waitcnt vmcnt(8)
	v_and_b32_e32 v39, 0xffff0000, v32
	v_lshlrev_b32_e32 v38, 16, v32
	v_and_b32_e32 v43, 0xffff0000, v33
	v_lshlrev_b32_e32 v42, 16, v33
	v_and_b32_e32 v33, 0xffff0000, v34
	v_lshlrev_b32_e32 v32, 16, v34
	v_and_b32_e32 v45, 0xffff0000, v35
	v_lshlrev_b32_e32 v44, 16, v35
	v_mov_b32_e32 v35, -1
	s_mov_b32 s21, 0
	v_mov_b32_e32 v110, 0xff800000
	s_mov_b32 s22, 0
	s_mov_b64 s[0:1], 0
	v_mov_b32_e32 v111, 0xff800000
	v_mov_b32_e32 v34, -1
	v_mov_b32_e32 v112, -1
	v_mov_b32_e32 v113, 0xff800000
	s_branch .LBB0_173
